# attention loop: second half-step common path straight-lined, its live certification between the QK MFMAs
# speedup vs baseline: 1.0341x; 1.0029x over previous
.Ldma_done:
	s_cmp_eq_u32 s87, s90
	s_cselect_b64 s[12:13], -1, 0
	s_or_b64 s[12:13], s[2:3], s[12:13]
	s_mov_b64 s[2:3], -1
	s_cbranch_scc1 .Lb_nform
	s_add_i32 s100, s88, 0x4000
	s_and_b32 s100, s100, 0xffff
	v_add_u32_e32 v82, s100, v186
	ds_read_b128 v[162:165], v82
	ds_read_b128 v[150:153], v82 offset:4096
	v_add_u32_e32 v82, s100, v188
	ds_read_b128 v[154:157], v82
	ds_read_b128 v[146:149], v82 offset:4096
	ds_read_b128 v[166:169], v189
	ds_read_b128 v[158:161], v192
	v_sub_f32_e32 v17, v17, v173
	v_sub_f32_e32 v16, v16, v173
	v_sub_f32_e32 v15, v15, v173
	v_sub_f32_e32 v14, v14, v173
	v_sub_f32_e32 v13, v13, v173
	v_sub_f32_e32 v12, v12, v173
	v_sub_f32_e32 v11, v11, v173
	v_sub_f32_e32 v10, v10, v173
	v_sub_f32_e32 v9, v9, v173
	v_sub_f32_e32 v8, v8, v173
	v_sub_f32_e32 v7, v7, v173
	v_sub_f32_e32 v6, v6, v173
	v_sub_f32_e32 v5, v5, v173
	v_sub_f32_e32 v4, v4, v173
	v_sub_f32_e32 v3, v3, v173
	v_sub_f32_e32 v2, v2, v173
	s_add_i32 s12, s90, 1
	s_add_i32 s2, s88, 0x4000
	s_and_b32 s88, s2, 0xffff
	s_cmp_ge_i32 s12, s83
	s_cbranch_scc1 .LBB0_339
	s_cmp_lt_u32 s90, 3
	s_mov_b64 s[2:3], -1
	s_cbranch_scc1 .LBB0_336
	s_waitcnt lgkmcnt(1)
	v_mfma_f32_32x32x16_bf16 v[98:113], v[162:165], v[166:169], v[2:17]
	s_cmp_lt_i32 s12, s82
	s_cselect_b64 vcc, -1, 0
	v_cndmask_b32_e32 v82, v197, v196, vcc
	v_pk_add_f32 v[96:97], v[82:83], v[16:17] op_sel_hi:[0,1]
	v_pk_add_f32 v[94:95], v[82:83], v[14:15] op_sel_hi:[0,1]
	v_pk_add_f32 v[92:93], v[82:83], v[12:13] op_sel_hi:[0,1]
	v_pk_add_f32 v[90:91], v[82:83], v[10:11] op_sel_hi:[0,1]
	v_pk_add_f32 v[88:89], v[82:83], v[8:9] op_sel_hi:[0,1]
	v_pk_add_f32 v[86:87], v[82:83], v[6:7] op_sel_hi:[0,1]
	v_pk_add_f32 v[84:85], v[82:83], v[4:5] op_sel_hi:[0,1]
	v_pk_add_f32 v[82:83], v[82:83], v[2:3] op_sel_hi:[0,1]
	v_max3_f32 v246, v130, v129, v137
	v_exp_f32_e32 v246, v246
	v_mfma_f32_32x32x16_bf16 v[82:97], v[150:153], v[166:169], v[82:97]
	s_waitcnt lgkmcnt(0)
	v_mfma_f32_32x32x16_bf16 v[98:113], v[154:157], v[158:161], v[98:113]
	v_mul_f32_e32 v246, 0x4f800000, v246
	v_cmp_ge_f32_e32 vcc, v246, v174
	v_mfma_f32_32x32x16_bf16 v[82:97], v[146:149], v[158:161], v[82:97]
	s_mov_b64 s[2:3], -1
	s_cmp_lg_u64 s[4:5], 0
	s_cbranch_scc1 .LBB0_345
	s_cmp_lt_u32 s90, 4
	s_cbranch_scc1 .Lq_fullB
	s_cmp_eq_u32 s99, 0
	s_cbranch_scc1 .Lq_fullB
	s_cmp_lg_u64 vcc, 0
	s_cbranch_scc1 .LBB0_345
	s_branch .Lq_fullB
.Lb_nform:
	s_and_b64 vcc, exec, s[12:13]
	s_cbranch_vccz .LBB0_324
	s_andn2_b64 vcc, exec, s[2:3]
	s_add_i32 s12, s90, 1
	s_cbranch_vccz .LBB0_325
